# MX: denominator split by k-block across the 8 v-slice blocks (ones tile only in ks=1 waves / owner wave), PP sums 8 partials; un-peeled last chunk step
# speedup vs baseline: 1.0105x; 1.0069x over previous
; #define MX_BAR() do { asm volatile("s_waitcnt lgkmcnt(0)" ::: "memory"); __builtin_amdgcn_s_barrier(); asm volatile("" ::: "memory"); } while (0)
; #define MX_LOADK(ch) do { const int r0_ = lrowb + (ch) * 64; const char* kr_ = (const char*)(kb + (size_t)r0_ * qpitch); \
;             _Pragma("unroll") for (int i = 0; i < 4; ++i) pk[i] = *(const u32x4*)(kr_ + i * qstep16 + voq); \
;             if (tid < 256) pv = *(const u32x4*)((const char*)(vb + (size_t)r0_ * NPC) + vov); } while (0)
; #define MX_STAGEQ() do { int ts_ = tid; \
;             _Pragma("unroll") for (int i = 0; i < 4; ++i) { const int idx = ts_ + 512 * i, row = idx >> 5, c16 = idx & 31; \
;                 *(LAS u32x4*)(lds + L_QI + row * QP + c16 * 16) = pq[i]; } } while (0)
; DI void phase_mixer(const Params& p, int seg, LAS unsigned char* lds, int G, int bid) {
;     ...
;         u32x4 pq[4], pk[4], pv; u32x2 pin[2]; float pden = 0.f, pcm = 0.f, pbc = 0.f, pmch = 0.f;
;         const unsigned voq = (unsigned)(((tid >> 5) * qpitch + (tid & 31) * 8) * 2);
;         const unsigned vov = (unsigned)(((tid >> 2) * NPC + (tid & 3) * 8) * 2);
;         const unsigned vop = (unsigned)(((16 * ((tid >> 6) & 3) + (tid & 15)) * NPC + 4 * ((tid & 63) >> 4)) * 2);
;         const size_t qstep16 = (size_t)16 * qpitch * 2;
;     ...
;         u32x2 cin[2]; float cden = 0.f, cemr = 1.f;
;         MX_LOADQ(0);
;         MX_LOADK(0);
;         MX_STAGEQ();
;         cin[0] = pin[0]; cin[1] = pin[1]; cden = pden; cemr = __expf(-(pbc + fmaxf(pmch, pcm)));
;         MX_BAR();
.LBB0_592:
	s_or_b64 exec, exec, s[50:51]
	s_and_b32 s31, s22, 3
	s_lshr_b32 s6, s8, 2
	s_lshl_b32 s50, s31, 12
	s_and_b32 s22, s39, 3
	s_and_b32 s18, s38, 0xfffffc00
	v_or_b32_e32 v2, s50, v161
	s_lshl_b32 s51, s22, 2
	s_and_b32 s6, s6, 7
	s_ashr_i32 s19, s18, 31
	v_lshl_or_b32 v3, v2, 4, s51
	s_lshl_b32 s6, s6, 6
	s_lshl_b64 s[18:19], s[18:19], 1
	v_or_b32_e32 v172, 0x500000, v3
	v_mul_hi_u32_u24_e32 v3, 0x4800, v2
	v_mul_u32_u24_e32 v2, 0x4800, v2
	s_lshl_b32 s33, s22, 9
	s_or_b32 s28, s18, s6
	v_or_b32_e32 v2, v146, v2
	s_or_b32 s28, s28, s33
	s_mov_b32 s29, s19
	v_lshl_add_u64 v[174:175], s[28:29], 0, v[2:3]
	s_lshl_b32 s84, s22, 4
	s_lshl_b64 s[28:29], s[26:27], 4
	s_add_u32 s35, s84, s28
	s_addc_u32 s22, 0, s29
	s_or_b32 s26, s6, s33
	s_mul_i32 s28, s31, 0x4800000
	s_or_b64 s[18:19], s[26:27], s[18:19]
	s_add_u32 s18, s18, s28
	s_addc_u32 s19, s19, 0
	s_lshl_b32 s6, s31, 13
	v_or_b32_e32 v2, s50, v227
	s_or_b32 s29, s6, 0xc0
	s_or_b32 s31, s6, 0xe0
	s_or_b32 s50, s6, 0xa0
	s_cmp_eq_u32 vcc_hi, 0
	v_lshl_add_u64 v[180:181], s[18:19], 0, v[150:151]
	s_cselect_b64 s[18:19], -1, 0
	s_and_b64 s[18:19], s[78:79], s[18:19]
	v_lshl_or_b32 v176, v2, 6, s84
	s_and_b64 s[84:85], s[18:19], s[44:45]
	s_or_b32 s18, s26, s28
	s_add_u32 s18, s18, s53
	s_addc_u32 s19, 0, 0
	s_bitset1_b32 s6, 7
	s_mul_i32 s6, s6, vcc_lo
	v_lshl_add_u64 v[182:183], s[18:19], 0, v[148:149]
	s_add_u32 s18, s23, s6
	s_addc_u32 s19, 0, 0
	s_add_u32 s18, s18, s33
	s_addc_u32 s19, s19, 0
	s_lshl_b32 s26, vcc_lo, 7
	s_mul_i32 s29, s29, vcc_lo
	v_lshl_add_u64 v[184:185], s[18:19], 0, v[0:1]
	s_add_u32 s18, s23, s29
	s_addc_u32 s19, 0, 0
	s_add_u32 s18, s18, s33
	s_addc_u32 s19, s19, 0
	s_mul_i32 s31, s31, vcc_lo
	v_lshl_add_u64 v[186:187], s[18:19], 0, v[0:1]
	s_add_u32 s18, s23, s31
	s_addc_u32 s19, 0, 0
	s_add_u32 s18, s18, s33
	s_addc_u32 s19, s19, 0
	s_mul_i32 s50, s50, vcc_lo
	v_lshl_add_u64 v[188:189], s[18:19], 0, v[0:1]
	s_add_u32 s18, s23, s50
	s_addc_u32 s19, 0, 0
	s_add_u32 s18, s18, s33
	s_addc_u32 s19, s19, 0
	s_add_u32 s6, s52, s6
	v_lshl_add_u64 v[190:191], s[18:19], 0, v[0:1]
	s_addc_u32 s19, 0, 0
	s_add_u32 s18, s6, s33
	s_addc_u32 s19, s19, 0
	s_add_u32 s6, s52, s29
	v_lshl_add_u64 v[192:193], s[18:19], 0, v[0:1]
	s_addc_u32 s19, 0, 0
	s_add_u32 s18, s6, s33
	s_addc_u32 s19, s19, 0
	v_lshl_or_b32 v2, v2, 4, s51
	s_add_u32 s6, s52, s31
	v_or_b32_e32 v178, 0x580000, v2
	s_waitcnt vmcnt(6)
	v_max_f32_e32 v2, v234, v234
	s_waitcnt vmcnt(4)
	v_max_f32_e32 v3, v235, v235
	v_lshl_add_u64 v[194:195], s[18:19], 0, v[0:1]
	s_addc_u32 s19, 0, 0
	v_max_f32_e32 v2, v3, v2
	s_add_u32 s18, s6, s33
	v_add_f32_e32 v2, v236, v2
	s_addc_u32 s19, s19, 0
	v_mul_f32_e32 v2, 0xbfb8aa3b, v2
	s_add_u32 s6, s52, s50
	ds_write_b128 v229, v[48:51]
	ds_write_b128 v230, v[52:55]
	ds_write_b128 v231, v[56:59]
	ds_write_b128 v232, v[60:63]
	v_exp_f32_e32 v237, v2
	v_lshl_add_u64 v[196:197], s[18:19], 0, v[0:1]
	s_addc_u32 s19, 0, 0
	s_waitcnt lgkmcnt(0)
	s_barrier
	s_add_u32 s18, s6, s33
	s_addc_u32 s19, s19, 0
	v_mov_b32_e32 v173, v1
	v_mov_b32_e32 v177, v1
	v_mov_b32_e32 v179, v1
	v_lshl_add_u64 v[198:199], s[18:19], 0, v[0:1]
	s_bfe_u32 s32, s8, 0x30002
	s_lshl_b32 s98, s32, 6
	v_add_u32_e32 v244, s98, v224
	v_add_u32_e32 v245, s98, v163
	v_lshrrev_b32_e32 v246, 6, v202
	s_lshl_b32 s98, s32, 2
	s_add_u32 s98, s92, s98
	s_addc_u32 s99, s93, 0
	s_sub_u32 s98, s98, 0x2000000
	s_subb_u32 s99, s99, 0
	s_add_u32 s100, s92, 0x580000
	s_addc_u32 s101, s93, 0
	v_readfirstlane_b32 vcc_lo, v246
	s_nop 3
	s_cmp_eq_u32 vcc_lo, s32
	s_cselect_b32 s32, 1, 0
	s_mov_b32 s23, 64
	v_mov_b64_e32 v[2:3], v[156:157]
	v_mov_b64_e32 v[200:201], v[154:155]
	s_andn2_b64 vcc, exec, s[78:79]
	v_mov_b32_e32 v160, v153
	s_cbranch_vccnz .LBB0_594

; #define LAS __attribute__((address_space(3)))
; DI void phase_mixer(const Params& p, int seg, LAS unsigned char* lds, int G, int bid) {
;     ...
;             bf16x8 qf[4], cf[3][4];
; #pragma unroll
;             for (int k4 = 0; k4 < 4; ++k4) qf[k4] = *(const LAS bf16x8*)(lds + L_QI + lq * QP + 64 * (4 * ks + k4) + 16 * g4);
; #pragma unroll
;             for (int v = 0; v < 3; ++v)
; #pragma unroll
;                 for (int k4 = 0; k4 < 4; ++k4) cf[v][k4] = *(const LAS bf16x8*)(lds + L_CI + (16 * v + i16) * QP + 64 * (4 * ks + k4) + 16 * g4);
;             __builtin_amdgcn_sched_barrier(0);
;             f32x4 num[3];
; #pragma unroll
;             for (int v = 0; v < 3; ++v) num[v] = (f32x4){0.f, 0.f, 0.f, 0.f};
;             if (ks == 0) { num[0] = (f32x4){bflo(cin[0].x), bfhi(cin[0].x), bflo(cin[0].y), bfhi(cin[0].y)};
;                 num[1] = (f32x4){bflo(cin[1].x), bfhi(cin[1].x), bflo(cin[1].y), bfhi(cin[1].y)}; num[2][0] = cden; }
; #pragma unroll
;             for (int k4 = 0; k4 < 4; ++k4)
; #pragma unroll
;                 for (int v = 0; v < 3; ++v) if (v < nvt) num[v] = __builtin_amdgcn_mfma_f32_16x16x32_bf16(cf[v][k4], qf[k4], num[v], 0, 0, 0);
;             if (ks == 1) {
; #pragma unroll
;                 for (int v = 0; v < 3; ++v)
; #pragma unroll
;                     for (int r = 0; r < 4; ++r) *(LAS float*)(lds + L_RED + ((li * 12 + v * 4 + r) * 64 + lnA) * 4) = num[v][r];
;             }
.LBB0_598:
	s_or_b64 exec, exec, s[50:51]
	v_add_u32_e32 v242, s89, v163
	v_add_u32_e32 v240, s89, v224
	v_add_u32_e32 v243, s97, v163
	v_add_u32_e32 v241, s97, v224
	s_andn2_b64 vcc, exec, s[70:71]
	s_cbranch_vccnz .Lmxa_r
	ds_read_b128 v[124:127], v244 offset:16896
	ds_read_b128 v[116:119], v245
.Lmxa_r:
	ds_read_b128 v[76:79], v242
	ds_read_b128 v[96:99], v240
	ds_read_b128 v[120:123], v240 offset:8448
	ds_read_b128 v[68:71], v242 offset:64
	ds_read_b128 v[80:83], v240 offset:64
	ds_read_b128 v[104:107], v240 offset:8512
	ds_read_b128 v[72:75], v242 offset:128
	ds_read_b128 v[84:87], v240 offset:128
	ds_read_b128 v[92:95], v240 offset:8576
	ds_read_b128 v[64:67], v243
	ds_read_b128 v[100:103], v241
	ds_read_b128 v[108:111], v241 offset:8448
	v_cndmask_b32_e64 v128, 0, 1, s[0:1]
	v_mov_b32_e32 v0, 0
	v_cmp_ne_u32_e64 s[50:51], 1, v128
	s_andn2_b64 vcc, exec, s[0:1]
	v_mov_b32_e32 v128, 0
	v_mov_b32_e32 v129, 0
	v_mov_b32_e32 v130, 0
	v_mov_b32_e32 v131, 0
	v_mov_b32_e32 v132, 0
	v_mov_b32_e32 v133, 0
	v_mov_b32_e32 v134, 0
	v_mov_b32_e32 v135, 0
	s_cbranch_vccnz .LBB0_600
	v_lshlrev_b32_e32 v132, 16, v200
	v_and_b32_e32 v133, 0xffff0000, v200
	v_lshlrev_b32_e32 v134, 16, v201
	v_and_b32_e32 v135, 0xffff0000, v201
	v_lshlrev_b32_e32 v128, 16, v2
	v_and_b32_e32 v129, 0xffff0000, v2
	v_lshlrev_b32_e32 v130, 16, v3
	v_and_b32_e32 v131, 0xffff0000, v3
.LBB0_600:
	v_mov_b32_e32 v2, v1
	v_mov_b32_e32 v3, v1
	s_andn2_b64 vcc, exec, s[70:71]
	s_waitcnt lgkmcnt(10)
	v_mfma_f32_16x16x32_bf16 v[96:99], v[96:99], v[76:79], v[132:135]
	s_waitcnt lgkmcnt(9)
	v_mfma_f32_16x16x32_bf16 v[120:123], v[120:123], v[76:79], v[128:131]
	s_waitcnt lgkmcnt(7)
	v_mfma_f32_16x16x32_bf16 v[80:83], v[80:83], v[68:71], v[96:99]
	s_waitcnt lgkmcnt(6)
	v_mfma_f32_16x16x32_bf16 v[96:99], v[104:107], v[68:71], v[120:123]
	s_waitcnt lgkmcnt(4)
	v_mfma_f32_16x16x32_bf16 v[76:79], v[84:87], v[72:75], v[80:83]
	s_waitcnt lgkmcnt(3)
	v_mfma_f32_16x16x32_bf16 v[80:83], v[92:95], v[72:75], v[96:99]
	s_waitcnt lgkmcnt(1)
	v_mfma_f32_16x16x32_bf16 v[72:75], v[100:103], v[64:67], v[76:79]
	s_waitcnt lgkmcnt(0)
	v_mfma_f32_16x16x32_bf16 v[68:71], v[108:111], v[64:67], v[80:83]
	s_cbranch_vccnz .LBB0_602
	s_nop 0
	v_mfma_f32_16x16x32_bf16 v[64:67], v[124:127], v[116:119], v[0:3]
	v_add_u32_e32 v88, s9, v219
	s_nop 1
	ds_write2st64_b32 v88, v72, v73 offset1:1
	ds_write2st64_b32 v88, v74, v75 offset0:2 offset1:3
	ds_write2st64_b32 v88, v68, v69 offset0:4 offset1:5
	ds_write2st64_b32 v88, v70, v71 offset0:6 offset1:7
	s_nop 1
	ds_write_b32 v88, v64 offset:2048

; #define LAS __attribute__((address_space(3)))
; DI void phase_mixer(const Params& p, int seg, LAS unsigned char* lds, int G, int bid) {
;     ...
;             if (ks == 0) {
; #pragma unroll
;                 for (int v = 0; v < 3; ++v)
; #pragma unroll
;                     for (int r = 0; r < 4; ++r) num[v][r] += *(const LAS float*)(lds + L_RED + ((li * 12 + v * 4 + r) * 64 + lnA) * 4);
;                 const int lrow = lrowb + ch * 64 + lq;
; #pragma unroll
;                 for (int v = 0; v < 2; ++v) { u32x2 w; w.x = cvt_pk_bf16(num[v][0], num[v][1]); w.y = cvt_pk_bf16(num[v][2], num[v][3]);
;                     *(u32x2*)(cellb + (size_t)lrow * NPC + 16 * v + 4 * g4) = w; }
;                 if (stab && vs == 0 && g4 == 0) dnb[(size_t)lrow * 4 + hh] = fmaxf(fabsf(num[2][0]), cemr);
;             }
.LBB0_606:
	s_or_b64 exec, exec, vcc
	s_waitcnt lgkmcnt(0)
	s_barrier
	s_and_b64 vcc, exec, s[50:51]
	s_cbranch_vccnz .LBB0_610
	v_add_u32_e32 v0, s11, v219
	ds_read2st64_b32 v[2:3], v0 offset1:1
	s_waitcnt lgkmcnt(0)
	v_add_f32_e32 v65, v72, v2
	v_add_f32_e32 v66, v73, v3
	ds_read2st64_b32 v[2:3], v0 offset0:2 offset1:3
	v_cvt_pk_bf16_f32 v66, v65, v66
	s_waitcnt lgkmcnt(0)
	v_add_f32_e32 v67, v74, v2
	v_add_f32_e32 v72, v75, v3
	ds_read2st64_b32 v[2:3], v0 offset0:4 offset1:5
	v_cvt_pk_bf16_f32 v67, v67, v72
	s_waitcnt lgkmcnt(0)
	v_add_f32_e32 v68, v68, v2
	v_add_f32_e32 v69, v69, v3
	ds_read2st64_b32 v[2:3], v0 offset0:6 offset1:7
	s_waitcnt lgkmcnt(0)
	v_add_f32_e32 v70, v70, v2
	v_add_f32_e32 v71, v71, v3
	v_lshl_add_u64 v[2:3], s[92:93], 0, v[174:175]
	v_add_co_u32_e32 v2, vcc, 0xc000000, v2
	s_nop 1
	v_addc_co_u32_e32 v3, vcc, 0, v3, vcc
	global_store_dwordx2 v[2:3], v[66:67], off
	v_cvt_pk_bf16_f32 v66, v68, v69
	v_cvt_pk_bf16_f32 v67, v70, v71
	global_store_dwordx2 v[2:3], v[66:67], off offset:32
	s_and_b64 s[52:53], s[78:79], s[44:45]
	s_and_saveexec_b64 vcc, s[52:53]
	s_cbranch_execz .LBB0_609
	ds_read_b32 v0, v0 offset:2048
	v_lshl_add_u64 v[2:3], v[172:173], 3, s[98:99]
	s_waitcnt lgkmcnt(0)
	v_add_f32_e32 v0, v239, v0
	global_store_dword v[2:3], v0, off
	s_and_b64 exec, exec, s[84:85]
	s_nop 1
	v_lshl_add_u64 v[2:3], s[100:101], 0, v[172:173]
	s_nop 0
	global_store_dword v[2:3], v237, off

; DI void phase_mixer(const Params& p, int seg, LAS unsigned char* lds, int G, int bid) {
;     ...
;             {
;                 s16x4 t0[4], t1r[4], tv[12];
;                 int lnB = lane;
;                 const int j16 = lnB & 15, h4 = lnB >> 4;
;                 const unsigned addr0 = ldsb + L_KI + (8 * h4 + (j16 >> 2)) * QP + (2 * wave) * 32 + 8 * (lnB & 3);
;                 const unsigned addrv = ldsb + L_VI + (8 * h4 + (j16 >> 2)) * VP2 + 8 * (lnB & 3);
;                 asm volatile("ds_read_b64_tr_b16 %0, %8\n\tds_read_b64_tr_b16 %1, %8 offset:2112\n\tds_read_b64_tr_b16 %2, %8 offset:16896\n\tds_read_b64_tr_b16 %3, %8 offset:19008\n\t"
;                              "ds_read_b64_tr_b16 %4, %8 offset:32\n\tds_read_b64_tr_b16 %5, %8 offset:2144\n\tds_read_b64_tr_b16 %6, %8 offset:16928\n\tds_read_b64_tr_b16 %7, %8 offset:19040\n\ts_waitcnt lgkmcnt(0)"
;                              : "=&v"(t0[0]), "=&v"(t0[1]), "=&v"(t0[2]), "=&v"(t0[3]), "=&v"(t1r[0]), "=&v"(t1r[1]), "=&v"(t1r[2]), "=&v"(t1r[3]) : "v"(addr0) : "memory");
;                 asm volatile("ds_read_b64_tr_b16 %0, %12\n\tds_read_b64_tr_b16 %1, %12 offset:448\n\tds_read_b64_tr_b16 %2, %12 offset:3584\n\tds_read_b64_tr_b16 %3, %12 offset:4032\n\t"
;                              "ds_read_b64_tr_b16 %4, %12 offset:32\n\tds_read_b64_tr_b16 %5, %12 offset:480\n\tds_read_b64_tr_b16 %6, %12 offset:3616\n\tds_read_b64_tr_b16 %7, %12 offset:4064\n\t"
;                              "ds_read_b64_tr_b16 %8, %12 offset:64\n\tds_read_b64_tr_b16 %9, %12 offset:512\n\tds_read_b64_tr_b16 %10, %12 offset:3648\n\tds_read_b64_tr_b16 %11, %12 offset:4096\n\ts_waitcnt lgkmcnt(0)"
;                              : "=&v"(tv[0]), "=&v"(tv[1]), "=&v"(tv[2]), "=&v"(tv[3]), "=&v"(tv[4]), "=&v"(tv[5]), "=&v"(tv[6]), "=&v"(tv[7]), "=&v"(tv[8]), "=&v"(tv[9]), "=&v"(tv[10]), "=&v"(tv[11]) : "v"(addrv) : "memory");
;                 __builtin_amdgcn_sched_barrier(0);
.LBB0_610:
	ds_read_b64_tr_b16 v[76:77], v221
	ds_read_b64_tr_b16 v[78:79], v221 offset:2112
	ds_read_b64_tr_b16 v[68:69], v221 offset:16896
	ds_read_b64_tr_b16 v[70:71], v221 offset:19008
	ds_read_b64_tr_b16 v[72:73], v221 offset:32
	ds_read_b64_tr_b16 v[74:75], v221 offset:2144
	ds_read_b64_tr_b16 v[64:65], v221 offset:16928
	ds_read_b64_tr_b16 v[66:67], v221 offset:19040
	s_waitcnt lgkmcnt(0)
	ds_read_b64_tr_b16 v[100:101], v222
	ds_read_b64_tr_b16 v[102:103], v222 offset:448
	ds_read_b64_tr_b16 v[88:89], v222 offset:3584
	ds_read_b64_tr_b16 v[90:91], v222 offset:4032
	ds_read_b64_tr_b16 v[96:97], v222 offset:32
	ds_read_b64_tr_b16 v[98:99], v222 offset:480
	ds_read_b64_tr_b16 v[84:85], v222 offset:3616
	ds_read_b64_tr_b16 v[86:87], v222 offset:4064
	s_waitcnt lgkmcnt(0)
	s_nop 0
	v_mfma_f32_16x16x32_bf16 v[12:15], v[76:79], v[100:103], v[12:15]
	s_and_b64 vcc, exec, s[42:43]
	s_cbranch_vccnz .Lmx_wm1
	s_waitcnt vmcnt(6)
	s_branch .Lmx_wm2

; #define MX_STAGEQ() do { int ts_ = tid; \
;             _Pragma("unroll") for (int i = 0; i < 4; ++i) { const int idx = ts_ + 512 * i, row = idx >> 5, c16 = idx & 31; \
;                 *(LAS u32x4*)(lds + L_QI + row * QP + c16 * 16) = pq[i]; } } while (0)
; DI void phase_mixer(const Params& p, int seg, LAS unsigned char* lds, int G, int bid) {
;     ...
; #pragma unroll
;                 for (int v = 0; v < 3; ++v) if (v < nvt) {
;                     const bf16x8 vb0 = __builtin_shufflevector(tv[4 * v], tv[4 * v + 1], 0, 1, 2, 3, 4, 5, 6, 7);
;                     C[0][v] = __builtin_amdgcn_mfma_f32_16x16x32_bf16(__builtin_shufflevector(t0[0], t0[1], 0, 1, 2, 3, 4, 5, 6, 7), vb0, C[0][v], 0, 0, 0);
;                     C[1][v] = __builtin_amdgcn_mfma_f32_16x16x32_bf16(__builtin_shufflevector(t1r[0], t1r[1], 0, 1, 2, 3, 4, 5, 6, 7), vb0, C[1][v], 0, 0, 0); }
; #pragma unroll
;                 for (int v = 0; v < 3; ++v) if (v < nvt) {
;                     const bf16x8 vb1 = __builtin_shufflevector(tv[4 * v + 2], tv[4 * v + 3], 0, 1, 2, 3, 4, 5, 6, 7);
;                     C[0][v] = __builtin_amdgcn_mfma_f32_16x16x32_bf16(__builtin_shufflevector(t0[2], t0[3], 0, 1, 2, 3, 4, 5, 6, 7), vb1, C[0][v], 0, 0, 0);
;                     C[1][v] = __builtin_amdgcn_mfma_f32_16x16x32_bf16(__builtin_shufflevector(t1r[2], t1r[3], 0, 1, 2, 3, 4, 5, 6, 7), vb1, C[1][v], 0, 0, 0); }
;             }
; #pragma unroll
;             for (int a = 0; a < 2; ++a)
; #pragma unroll
;                 for (int v = 0; v < 3; ++v) C[a][v] = C[a][v] * g_c;
;             MX_WRITE_CIMG(1.0f);
;             if (ch + 1 < NCH) { MX_STAGEQ(); cin[0] = pin[0]; cin[1] = pin[1]; cden = pden; cemr = __expf(-(pbc + fmaxf(pmch, pcm))); }
.Lmx_wm2:
	v_max_f32_e32 v0, v234, v234
	s_add_u32 s35, s35, 64
	s_addc_u32 s22, s22, 0
	v_mfma_f32_16x16x32_bf16 v[8:11], v[76:79], v[96:99], v[8:11]
	s_add_i32 s23, s23, -1
	s_mov_b64 s[18:19], 0x1000
	v_lshl_add_u64 v[172:173], v[172:173], 0, s[54:55]
	v_lshl_add_u64 v[174:175], v[174:175], 0, s[56:57]
	v_lshl_add_u64 v[176:177], v[176:177], 0, s[18:19]
	v_lshl_add_u64 v[178:179], v[178:179], 0, s[54:55]
	v_mfma_f32_16x16x32_bf16 v[20:23], v[72:75], v[100:103], v[20:23]
	v_lshl_add_u64 v[182:183], v[182:183], 0, s[56:57]
	v_lshl_add_u64 v[180:181], v[180:181], 0, s[56:57]
	v_lshl_add_u64 v[184:185], v[184:185], 0, s[26:27]
	v_mfma_f32_16x16x32_bf16 v[28:31], v[72:75], v[96:99], v[28:31]
	v_lshl_add_u64 v[186:187], v[186:187], 0, s[26:27]
	v_lshl_add_u64 v[188:189], v[188:189], 0, s[26:27]
	v_lshl_add_u64 v[190:191], v[190:191], 0, s[26:27]
	v_mfma_f32_16x16x32_bf16 v[12:15], v[68:71], v[88:91], v[12:15]
	v_lshl_add_u64 v[192:193], v[192:193], 0, s[26:27]
	v_lshl_add_u64 v[194:195], v[194:195], 0, s[26:27]
	v_lshl_add_u64 v[196:197], v[196:197], 0, s[26:27]
	s_nop 4
	v_pk_mul_f32 v[14:15], v[158:159], v[14:15] op_sel_hi:[0,1]
	v_pk_mul_f32 v[12:13], v[158:159], v[12:13] op_sel_hi:[0,1]
	v_mfma_f32_16x16x32_bf16 v[8:11], v[68:71], v[84:87], v[8:11]
	v_cvt_pk_bf16_f32 v2, v12, v13
	v_cvt_pk_bf16_f32 v3, v14, v15
	ds_write_b64 v228, v[2:3]
	v_lshl_add_u64 v[198:199], v[198:199], 0, s[26:27]
	s_nop 3
	v_pk_mul_f32 v[10:11], v[158:159], v[10:11] op_sel_hi:[0,1]
	v_pk_mul_f32 v[8:9], v[158:159], v[8:9] op_sel_hi:[0,1]
	v_mfma_f32_16x16x32_bf16 v[20:23], v[64:67], v[88:91], v[20:23]
	v_cvt_pk_bf16_f32 v2, v8, v9
	v_mfma_f32_16x16x32_bf16 v[28:31], v[64:67], v[84:87], v[28:31]
	v_cvt_pk_bf16_f32 v3, v10, v11
	s_nop 4
	v_pk_mul_f32 v[22:23], v[158:159], v[22:23] op_sel_hi:[0,1]
	v_pk_mul_f32 v[20:21], v[158:159], v[20:21] op_sel_hi:[0,1]
	ds_write_b64 v228, v[2:3] offset:8448
	v_pk_mul_f32 v[30:31], v[158:159], v[30:31] op_sel_hi:[0,1]
	v_pk_mul_f32 v[28:29], v[158:159], v[28:29] op_sel_hi:[0,1]
	v_cvt_pk_bf16_f32 v2, v20, v21
	v_cvt_pk_bf16_f32 v3, v22, v23
	ds_write_b64 v233, v[2:3]
	v_cvt_pk_bf16_f32 v2, v28, v29
	v_cvt_pk_bf16_f32 v3, v30, v31
	ds_write_b64 v233, v[2:3] offset:8448
	s_cmp_lg_u32 s32, 0
	s_cbranch_scc0 .Lmxb_noown
	ds_read_b64_tr_b16 v[92:93], v222 offset:64
	ds_read_b64_tr_b16 v[94:95], v222 offset:512
	ds_read_b64_tr_b16 v[80:81], v222 offset:3648
	ds_read_b64_tr_b16 v[82:83], v222 offset:4096
	s_waitcnt lgkmcnt(0)
	v_mfma_f32_16x16x32_bf16 v[16:19], v[76:79], v[92:95], v[16:19]
	v_mfma_f32_16x16x32_bf16 v[24:27], v[72:75], v[92:95], v[24:27]
	v_mfma_f32_16x16x32_bf16 v[16:19], v[68:71], v[80:83], v[16:19]
	v_mfma_f32_16x16x32_bf16 v[24:27], v[64:67], v[80:83], v[24:27]
	s_nop 7
	s_nop 3
	v_pk_mul_f32 v[18:19], v[158:159], v[18:19] op_sel_hi:[0,1]
	v_pk_mul_f32 v[16:17], v[158:159], v[16:17] op_sel_hi:[0,1]
	v_pk_mul_f32 v[26:27], v[158:159], v[26:27] op_sel_hi:[0,1]
	v_pk_mul_f32 v[24:25], v[158:159], v[24:25] op_sel_hi:[0,1]
	v_cvt_pk_bf16_f32 v2, v16, v17
	v_cvt_pk_bf16_f32 v3, v18, v19
	ds_write_b64 v228, v[2:3] offset:16896
	v_cvt_pk_bf16_f32 v2, v24, v25
	v_cvt_pk_bf16_f32 v3, v26, v27
	ds_write_b64 v233, v[2:3] offset:16896
.Lmxb_noown:
	s_cbranch_vccnz .Lmx_wq1
	ds_write_b128 v229, v[48:51]
	ds_write_b128 v230, v[52:55]
	s_waitcnt vmcnt(5)
	ds_write_b128 v231, v[56:59]
	s_waitcnt vmcnt(4)
	ds_write_b128 v232, v[60:63]
	s_branch .Lmx_wq2

; #define MX_BAR() do { asm volatile("s_waitcnt lgkmcnt(0)" ::: "memory"); __builtin_amdgcn_s_barrier(); asm volatile("" ::: "memory"); } while (0)
; #define MX_STAGEQ() do { int ts_ = tid; \
;             _Pragma("unroll") for (int i = 0; i < 4; ++i) { const int idx = ts_ + 512 * i, row = idx >> 5, c16 = idx & 31; \
;                 *(LAS u32x4*)(lds + L_QI + row * QP + c16 * 16) = pq[i]; } } while (0)
; DI void phase_mixer(const Params& p, int seg, LAS unsigned char* lds, int G, int bid) {
;     ...
;             if (ch + 1 < NCH) { MX_STAGEQ(); cin[0] = pin[0]; cin[1] = pin[1]; cden = pden; cemr = __expf(-(pbc + fmaxf(pmch, pcm))); }
;             MX_BAR();
;             g_c = g_n;
;         }
;         if (seg + 1 < NSEG) {
; #pragma unroll
;             for (int a = 0; a < 2; ++a)
; #pragma unroll
;                 for (int v = 0; v < 3; ++v) *(f32x4*)(csave + ((size_t)item * 6 + a * 3 + v) * 2048 + tid * 4) = C[a][v];
;         }
;         __syncthreads();
.Lmx_wq2:
	v_max_f32_e32 v2, v235, v235
	v_max_f32_e32 v0, v2, v0
	v_add_f32_e32 v0, v236, v0
	v_mul_f32_e32 v0, 0xbfb8aa3b, v0
	v_exp_f32_e32 v237, v0
	s_waitcnt lgkmcnt(0)
	s_barrier
	s_cmp_eq_u32 s23, 0
	s_cbranch_scc1 .LBB0_612
	v_mov_b32_e32 v158, v160
	v_mov_b64_e32 v[2:3], v[156:157]
	v_mov_b64_e32 v[200:201], v[154:155]
	v_mov_b32_e32 v239, v238
	s_andn2_b64 vcc, exec, s[78:79]
	v_mov_b32_e32 v160, v153
	s_cbranch_vccz .LBB0_593
	s_branch .LBB0_594
.LBB0_612:
	v_readlane_b32 s18, v250, 35
	v_readlane_b32 s19, v250, 36
	s_andn2_b64 vcc, exec, s[18:19]
	v_swap_b32 v12, v28
	v_swap_b32 v13, v29
	v_swap_b32 v14, v30
	v_swap_b32 v15, v31
	v_swap_b32 v8, v24
	v_swap_b32 v9, v25
	v_swap_b32 v10, v26
	v_swap_b32 v11, v27
	v_swap_b32 v16, v20
	v_swap_b32 v17, v21
	v_swap_b32 v18, v22
	v_swap_b32 v19, v23
	s_cbranch_vccnz .LBB0_573
	v_mad_i64_i32 v[2:3], s[18:19], s8, v215, v[138:139]
	global_store_dwordx4 v[2:3], v[28:31], off
	s_nop 1
	v_add_co_u32_e32 v28, vcc, 0x2000, v2
	s_nop 1
	v_addc_co_u32_e32 v29, vcc, 0, v3, vcc
	global_store_dwordx4 v[28:29], v[24:27], off
	s_nop 1
	v_add_co_u32_e32 v24, vcc, 0x4000, v2
	s_nop 1
	v_addc_co_u32_e32 v25, vcc, 0, v3, vcc
	global_store_dwordx4 v[24:25], v[20:23], off
	s_nop 1
	v_add_co_u32_e32 v20, vcc, 0x6000, v2
	s_nop 1
	v_addc_co_u32_e32 v21, vcc, 0, v3, vcc
	global_store_dwordx4 v[20:21], v[16:19], off
	s_nop 1
	v_add_co_u32_e32 v16, vcc, 0x8000, v2
	s_nop 1
	v_addc_co_u32_e32 v17, vcc, 0, v3, vcc
	v_add_co_u32_e32 v2, vcc, 0xa000, v2
	global_store_dwordx4 v[16:17], v[12:15], off
	s_nop 0
	v_addc_co_u32_e32 v3, vcc, 0, v3, vcc
	global_store_dwordx4 v[2:3], v[8:11], off
	s_branch .LBB0_573

; DI void phase_post(const Params& p, int l, int G, int bid) {
;     int tid = threadIdx.x; asm volatile("" : "+v"(tid));
;     const int lane = tid & 63, wave = tid >> 6;
;     bf16_t* P = (bf16_t*)(p.ws + WS_P);
;     const float* dnb = (const float*)(p.ws + WS_DN);
;     const int hh = lane >> 4;
;     f32x4 gnm[4], gnr[4];
; #pragma unroll
;     for (int q = 0; q < 4; ++q) { gnm[q] = *(const f32x4*)(p.gn_m + l * 1024 + 16 * lane + 4 * q); gnr[q] = *(const f32x4*)(p.gn_r + l * 1024 + 16 * lane + 4 * q); }
;     u32x4 nc0, nc1, nz0, nz1, no0 = {0u, 0u, 0u, 0u}, no1 = {0u, 0u, 0u, 0u}; float ndn = 1.f;
;     ...
;     if (bid * 8 + wave < MSEG * 2) PP_LOAD(bid * 8 + wave);
;     for (int it = bid * 8 + wave; it < MSEG * 2; it += G * 8) {
;         const int lrow = it >> 1, grp = it & 1;
;         bf16_t* cp = P + (size_t)lrow * NPC + grp * 1024 + 16 * lane;
;         const u32x4 c0 = nc0, c1 = nc1, z0 = nz0, z1 = nz1, o0 = no0, o1 = no1;
;         const float inv = (grp == 0) ? 1.0f / ndn : 1.f;
;         if (it + G * 8 < MSEG * 2) PP_LOAD(it + G * 8);
.LBB0_691:
.LBB0_692:
	v_readlane_b32 s0, v252, 4
	v_readlane_b32 s1, v252, 5
	s_cmp_ge_i32 s88, s0
	s_cselect_b64 s[0:1], -1, 0
	s_cmp_lt_i32 s88, s33
	s_cselect_b64 s[8:9], -1, 0
	s_and_b64 s[0:1], s[0:1], s[8:9]
	s_andn2_b64 vcc, exec, s[0:1]
	v_readlane_b32 s0, v250, 58
	s_add_i32 s26, s0, 6
	s_cbranch_vccnz .LBB0_772
	s_waitcnt vmcnt(0)
	v_mov_b32_e32 v2, v202
	v_readlane_b32 s0, v250, 2
	v_ashrrev_i32_e32 v0, 6, v2
	v_readlane_b32 s1, v250, 3
	v_add_u32_e32 v60, s0, v0
	s_mov_b32 s0, 0x8000
	v_cmp_gt_i32_e32 vcc, s0, v60
	s_and_saveexec_b64 s[42:43], vcc
	s_cbranch_execz .LBB0_704
	v_and_b32_e32 v3, 63, v2
	v_ashrrev_i32_e32 v36, 1, v60
	v_mov_b64_e32 v[4:5], s[24:25]
	v_bfe_u32 v35, v2, 6, 1
	s_add_u32 s98, s92, 0x800000
	s_addc_u32 s99, s93, 0
	s_add_u32 s100, s92, 0xa80000
	s_addc_u32 s101, s93, 0
	v_bfe_u32 v131, v202, 4, 2
	v_lshlrev_b32_e32 v131, 2, v131
	v_mad_i64_i32 v[4:5], s[0:1], v36, s96, v[4:5]
	v_lshlrev_b32_e32 v0, 5, v3
	v_lshl_add_u64 v[4:5], v[4:5], 0, v[0:1]
	v_lshlrev_b32_e32 v0, 11, v35
	v_cmp_eq_u32_e64 s[40:41], 0, v35
	v_lshl_add_u64 v[6:7], v[4:5], 0, v[0:1]
	v_mov_b32_e32 v51, v1
	v_cndmask_b32_e64 v0, v216, v217, s[40:41]
	v_lshlrev_b32_e32 v50, 1, v0
	v_lshl_add_u64 v[4:5], v[4:5], 0, v[50:51]
	global_load_dwordx4 v[30:33], v[6:7], off offset:16
	global_load_dwordx4 v[26:29], v[6:7], off
	global_load_dwordx4 v[22:25], v[4:5], off offset:16
	global_load_dwordx4 v[18:21], v[4:5], off
	v_lshlrev_b32_e32 v38, 4, v3
	v_and_b32_e32 v0, 64, v2
	v_bfe_u32 v34, v2, 4, 2
	v_cmp_ne_u32_e32 vcc, 0, v0
	v_lshlrev_b32_e32 v0, 2, v38
	s_and_saveexec_b64 s[0:1], vcc
	s_xor_b64 s[0:1], exec, s[0:1]
	s_cbranch_execz .LBB0_696
	v_readlane_b32 s8, v250, 33
	v_readlane_b32 s9, v250, 34
	s_nop 4
	global_load_dwordx4 v[2:5], v0, s[8:9] offset:48
	global_load_dwordx4 v[6:9], v0, s[8:9] offset:32
	global_load_dwordx4 v[10:13], v0, s[8:9] offset:16
	global_load_dwordx4 v[14:17], v0, s[8:9]
.LBB0_696:
	s_or_saveexec_b64 s[0:1], s[0:1]
	v_mov_b32_e32 v66, 1.0
	s_xor_b64 exec, exec, s[0:1]
	s_cbranch_execz .LBB0_698
	v_readlane_b32 s8, v250, 31
	v_readlane_b32 s9, v250, 32
	s_nop 4
	global_load_dwordx4 v[2:5], v0, s[8:9] offset:48
	global_load_dwordx4 v[6:9], v0, s[8:9] offset:32
	global_load_dwordx4 v[10:13], v0, s[8:9] offset:16
	global_load_dwordx4 v[14:17], v0, s[8:9]
	v_lshlrev_b32_e32 v130, 4, v36
	v_lshl_add_u32 v130, v34, 2, v130
	v_lshlrev_b32_e32 v129, 3, v130
	global_load_dwordx4 v[120:123], v129, s[98:99]
	global_load_dwordx4 v[124:127], v129, s[98:99] offset:16
	global_load_dword v128, v130, s[100:101]
.LBB0_698:
	s_or_b64 exec, exec, s[0:1]
	v_readlane_b32 s0, v251, 38
	v_lshlrev_b32_e32 v0, 2, v34
	v_readlane_b32 s1, v251, 39
	v_lshlrev_b32_e32 v35, 10, v35
	v_lshlrev_b32_e32 v36, 1, v38
	v_lshl_add_u64 v[54:55], s[0:1], 0, v[0:1]
	v_and_b32_e32 v0, 64, v203
	v_add_u32_e32 v38, 64, v0
	v_lshlrev_b32_e32 v0, 1, v35
	v_mov_b32_e32 v37, v1
	v_lshl_add_u64 v[34:35], s[24:25], 0, v[0:1]
	v_lshl_add_u64 v[56:57], v[34:35], 0, v[36:37]
	v_xor_b32_e32 v34, 1, v203
	v_cmp_lt_i32_e32 vcc, v34, v38
	v_lshl_add_u64 v[52:53], s[24:25], 0, v[36:37]
	s_waitcnt vmcnt(1)
	v_mov_b64_e32 v[44:45], v[24:25]
	v_cndmask_b32_e32 v34, v203, v34, vcc
	v_lshlrev_b32_e32 v61, 2, v34
	v_xor_b32_e32 v34, 2, v203
	v_cmp_lt_i32_e32 vcc, v34, v38
	s_waitcnt vmcnt(0)
	v_add_f32_e32 v120, v120, v121
	v_add_f32_e32 v122, v122, v123
	v_add_f32_e32 v124, v124, v125
	v_add_f32_e32 v126, v126, v127
	v_add_f32_e32 v120, v120, v122
	v_add_f32_e32 v124, v124, v126
	v_add_f32_e32 v120, v120, v124
	v_max_f32_e64 v120, |v120|, v128
	v_cndmask_b32_e64 v66, v66, v120, s[40:41]
	v_mov_b64_e32 v[48:49], v[20:21]
	s_mov_b64 s[44:45], 0
	v_cndmask_b32_e32 v34, v203, v34, vcc
	v_lshlrev_b32_e32 v62, 2, v34
	v_xor_b32_e32 v34, 4, v203
	v_cmp_lt_i32_e32 vcc, v34, v38
	v_mov_b32_e32 v51, v66
	v_mov_b64_e32 v[42:43], v[22:23]
	v_cndmask_b32_e32 v34, v203, v34, vcc
	v_lshlrev_b32_e32 v63, 2, v34
	v_xor_b32_e32 v34, 8, v203
	v_cmp_lt_i32_e32 vcc, v34, v38
	v_mov_b64_e32 v[40:41], v[28:29]
	v_mov_b64_e32 v[46:47], v[18:19]
	v_cndmask_b32_e32 v34, v203, v34, vcc
	v_lshlrev_b32_e32 v64, 2, v34
	v_mov_b64_e32 v[36:37], v[32:33]
	v_mov_b64_e32 v[34:35], v[30:31]
	v_mov_b64_e32 v[38:39], v[26:27]
	s_branch .LBB0_701

; DI void phase_post(const Params& p, int l, int G, int bid) {
;     ...
;         const float inv = (grp == 0) ? 1.0f / ndn : 1.f;
;         if (it + G * 8 < MSEG * 2) PP_LOAD(it + G * 8);
;         float h[16], sum = 0.f;
; #pragma unroll
;         for (int q = 0; q < 4; ++q) { h[2 * q] = bflo(c0[q]) * inv; h[2 * q + 1] = bfhi(c0[q]) * inv; h[8 + 2 * q] = bflo(c1[q]) * inv; h[8 + 2 * q + 1] = bfhi(c1[q]) * inv; }
; #pragma unroll
;         for (int e = 0; e < 16; ++e) sum += h[e];
; #pragma unroll
;         for (int o = 1; o < 16; o <<= 1) sum += __shfl_xor(sum, o);
;         const float mu = sum * (1.f / 256.f);
;         float q2 = 0.f;
; #pragma unroll
;         for (int e = 0; e < 16; ++e) { h[e] -= mu; q2 += h[e] * h[e]; }
; #pragma unroll
;         for (int o = 1; o < 16; o <<= 1) q2 += __shfl_xor(q2, o);
.LBB0_700:
	s_or_b64 exec, exec, s[0:1]
	v_div_scale_f32 v58, s[0:1], v66, v66, 1.0
	v_rcp_f32_e32 v59, v58
	v_div_scale_f32 v67, vcc, 1.0, v66, 1.0
	v_lshlrev_b32_e32 v88, 16, v26
	v_fma_f32 v68, -v58, v59, 1.0
	v_fmac_f32_e32 v59, v68, v59
	v_mul_f32_e32 v68, v67, v59
	v_fma_f32 v69, -v58, v68, v67
	v_fmac_f32_e32 v68, v69, v59
	v_fma_f32 v58, -v58, v68, v67
	v_div_fmas_f32 v58, v58, v59, v68
	v_div_fixup_f32 v58, v58, v66, 1.0
	v_cndmask_b32_e64 v58, 1.0, v58, s[40:41]
	v_and_b32_e32 v89, 0xffff0000, v26
	v_lshlrev_b32_e32 v84, 16, v27
	v_and_b32_e32 v85, 0xffff0000, v27
	v_pk_mul_f32 v[26:27], v[58:59], v[88:89] op_sel_hi:[0,1]
	v_add_f32_e32 v26, 0, v26
	v_pk_mul_f32 v[86:87], v[58:59], v[84:85] op_sel_hi:[0,1]
	v_add_f32_e32 v26, v27, v26
	v_lshlrev_b32_e32 v82, 16, v28
	v_and_b32_e32 v83, 0xffff0000, v28
	v_add_f32_e32 v26, v86, v26
	v_lshlrev_b32_e32 v78, 16, v29
	v_and_b32_e32 v79, 0xffff0000, v29
	v_pk_mul_f32 v[28:29], v[58:59], v[82:83] op_sel_hi:[0,1]
	v_add_f32_e32 v26, v87, v26
	v_add_f32_e32 v26, v28, v26
	v_pk_mul_f32 v[80:81], v[58:59], v[78:79] op_sel_hi:[0,1]
	v_add_f32_e32 v26, v29, v26
	v_lshlrev_b32_e32 v76, 16, v30
	v_and_b32_e32 v77, 0xffff0000, v30
	v_add_f32_e32 v26, v80, v26
	v_lshlrev_b32_e32 v72, 16, v31
	v_and_b32_e32 v73, 0xffff0000, v31
	v_pk_mul_f32 v[30:31], v[58:59], v[76:77] op_sel_hi:[0,1]
	v_add_f32_e32 v26, v81, v26
	v_add_f32_e32 v26, v30, v26
	v_pk_mul_f32 v[74:75], v[58:59], v[72:73] op_sel_hi:[0,1]
	v_add_f32_e32 v26, v31, v26
	v_lshlrev_b32_e32 v70, 16, v32
	v_and_b32_e32 v71, 0xffff0000, v32
	v_add_f32_e32 v26, v74, v26
	v_lshlrev_b32_e32 v66, 16, v33
	v_and_b32_e32 v67, 0xffff0000, v33
	v_pk_mul_f32 v[32:33], v[58:59], v[70:71] op_sel_hi:[0,1]
	v_add_f32_e32 v26, v75, v26
	v_add_f32_e32 v26, v32, v26
	v_pk_mul_f32 v[68:69], v[58:59], v[66:67] op_sel_hi:[0,1]
	v_add_f32_e32 v26, v33, v26
	v_add_f32_e32 v26, v68, v26
	v_add_f32_e32 v26, v69, v26
	ds_bpermute_b32 v27, v61, v26
	s_waitcnt lgkmcnt(0)
	v_add_f32_e32 v26, v26, v27
	ds_bpermute_b32 v27, v62, v26
	s_waitcnt lgkmcnt(0)
	v_add_f32_e32 v26, v26, v27
	ds_bpermute_b32 v27, v63, v26
	s_waitcnt lgkmcnt(0)
	v_add_f32_e32 v26, v26, v27
	ds_bpermute_b32 v27, v64, v26
	s_waitcnt lgkmcnt(0)
	v_add_f32_e32 v26, v26, v27
	v_mul_f32_e32 v26, 0x3b800000, v26
	v_pk_fma_f32 v[28:29], v[58:59], v[88:89], v[26:27] op_sel_hi:[0,1,0] neg_lo:[0,0,1] neg_hi:[0,0,1]
	v_pk_mul_f32 v[30:31], v[28:29], v[28:29]
	v_pk_fma_f32 v[32:33], v[58:59], v[84:85], v[26:27] op_sel_hi:[0,1,0] neg_lo:[0,0,1] neg_hi:[0,0,1]
	v_pk_mul_f32 v[68:69], v[32:33], v[32:33]
	v_add_f32_e32 v30, v30, v31
	v_pk_fma_f32 v[74:75], v[58:59], v[82:83], v[26:27] op_sel_hi:[0,1,0] neg_lo:[0,0,1] neg_hi:[0,0,1]
	v_add_f32_e32 v30, v68, v30
	v_pk_mul_f32 v[80:81], v[74:75], v[74:75]
	v_add_f32_e32 v30, v69, v30
	v_pk_fma_f32 v[78:79], v[58:59], v[78:79], v[26:27] op_sel_hi:[0,1,0] neg_lo:[0,0,1] neg_hi:[0,0,1]
	v_add_f32_e32 v30, v80, v30
	v_pk_mul_f32 v[82:83], v[78:79], v[78:79]
	v_add_f32_e32 v30, v81, v30
	v_pk_fma_f32 v[76:77], v[58:59], v[76:77], v[26:27] op_sel_hi:[0,1,0] neg_lo:[0,0,1] neg_hi:[0,0,1]
	v_add_f32_e32 v30, v82, v30
	v_pk_mul_f32 v[84:85], v[76:77], v[76:77]
	v_add_f32_e32 v30, v83, v30
	v_pk_fma_f32 v[72:73], v[58:59], v[72:73], v[26:27] op_sel_hi:[0,1,0] neg_lo:[0,0,1] neg_hi:[0,0,1]
	v_add_f32_e32 v30, v84, v30
	v_pk_mul_f32 v[86:87], v[72:73], v[72:73]
	v_add_f32_e32 v30, v85, v30
	v_pk_fma_f32 v[70:71], v[58:59], v[70:71], v[26:27] op_sel_hi:[0,1,0] neg_lo:[0,0,1] neg_hi:[0,0,1]
	v_add_f32_e32 v30, v86, v30
	v_pk_mul_f32 v[88:89], v[70:71], v[70:71]
	v_add_f32_e32 v30, v87, v30
	v_pk_fma_f32 v[26:27], v[58:59], v[66:67], v[26:27] op_sel_hi:[0,1,0] neg_lo:[0,0,1] neg_hi:[0,0,1]
	v_add_f32_e32 v30, v88, v30
	v_pk_mul_f32 v[58:59], v[26:27], v[26:27]
	v_add_f32_e32 v30, v89, v30
	v_add_f32_e32 v30, v58, v30
	v_add_f32_e32 v30, v59, v30
	ds_bpermute_b32 v31, v61, v30
	v_ashrrev_i32_e32 v58, 1, v60
	v_and_b32_e32 v59, 0xffff0000, v25
	v_and_b32_e32 v67, 0xffff0000, v24
	v_and_b32_e32 v69, 0xffff0000, v22
	s_waitcnt lgkmcnt(0)
	v_add_f32_e32 v60, v30, v31
	ds_bpermute_b32 v66, v62, v60
	v_mad_i64_i32 v[30:31], s[0:1], v58, s96, v[56:57]
	v_lshlrev_b32_e32 v58, 16, v25
	v_and_b32_e32 v25, 0xffff0000, v23
	s_waitcnt lgkmcnt(0)
	v_add_f32_e32 v60, v60, v66
	ds_bpermute_b32 v68, v63, v60
	v_lshlrev_b32_e32 v66, 16, v24
	v_lshlrev_b32_e32 v24, 16, v23
	v_and_b32_e32 v23, 0xffff0000, v21
	s_mov_b32 s0, 0xf800000
	s_waitcnt lgkmcnt(0)
; DI void phase_post(const Params& p, int l, int G, int bid) {
;     ...
;         const float rstd = 1.0f / sqrtf(q2 * (1.f / 256.f) + EPS);
;         float y[16];
; #pragma unroll
;         for (int q = 0; q < 4; ++q) {
;             const f32x4 gn = (grp == 0) ? gnm[q] : gnr[q];
;             const unsigned zz0 = (q < 2) ? z0[2 * q] : z1[2 * q - 4], zz1 = (q < 2) ? z0[2 * q + 1] : z1[2 * q - 3];
;             const unsigned oo0 = (q < 2) ? o0[2 * q] : o1[2 * q - 4], oo1 = (q < 2) ? o0[2 * q + 1] : o1[2 * q - 3];
;             const float zv[4] = {bflo(zz0), bfhi(zz0), bflo(zz1), bfhi(zz1)};
;             const float ov[4] = {bflo(oo0), bfhi(oo0), bflo(oo1), bfhi(oo1)};
; #pragma unroll
;             for (int e = 0; e < 4; ++e) y[4 * q + e] = (h[4 * q + e] * rstd * gn[e]) * zv[e];
;         }
;         u32x4 w0, w1;
;         w0.x = cvt_pk_bf16(y[0], y[1]); w0.y = cvt_pk_bf16(y[2], y[3]); w0.z = cvt_pk_bf16(y[4], y[5]); w0.w = cvt_pk_bf16(y[6], y[7]);
;         w1.x = cvt_pk_bf16(y[8], y[9]); w1.y = cvt_pk_bf16(y[10], y[11]); w1.z = cvt_pk_bf16(y[12], y[13]); w1.w = cvt_pk_bf16(y[14], y[15]);
;         *(u32x4*)cp = w0; *(u32x4*)(cp + 8) = w1;
;     }
	v_add_f32_e32 v60, v60, v68
	ds_bpermute_b32 v80, v64, v60
	v_lshlrev_b32_e32 v68, 16, v22
	v_lshlrev_b32_e32 v22, 16, v21
	v_and_b32_e32 v81, 0xffff0000, v20
	s_waitcnt lgkmcnt(0)
	v_add_f32_e32 v21, v60, v80
	v_fmamk_f32 v21, v21, 0x3b800000, v204
	v_mul_f32_e32 v60, 0x4f800000, v21
	v_cmp_gt_f32_e32 vcc, s0, v21
	v_lshlrev_b32_e32 v80, 16, v20
	v_lshlrev_b32_e32 v20, 16, v19
	v_cndmask_b32_e32 v21, v21, v60, vcc
	v_sqrt_f32_e32 v60, v21
	s_nop 0
	v_add_u32_e32 v82, -1, v60
	v_fma_f32 v83, -v82, v60, v21
	v_cmp_ge_f32_e64 s[0:1], 0, v83
	v_add_u32_e32 v83, 1, v60
	s_nop 0
	v_cndmask_b32_e64 v82, v60, v82, s[0:1]
	v_fma_f32 v60, -v83, v60, v21
	v_cmp_lt_f32_e64 s[0:1], 0, v60
	s_nop 1
	v_cndmask_b32_e64 v60, v82, v83, s[0:1]
	v_mul_f32_e32 v82, 0x37800000, v60
	v_cndmask_b32_e32 v60, v60, v82, vcc
	v_cmp_class_f32_e32 vcc, v21, v205
	v_lshlrev_b32_e32 v82, 16, v18
	v_and_b32_e32 v83, 0xffff0000, v18
	v_cndmask_b32_e32 v60, v60, v21, vcc
	v_div_scale_f32 v84, s[0:1], v60, v60, 1.0
	v_rcp_f32_e32 v85, v84
	v_and_b32_e32 v21, 0xffff0000, v19
	v_fma_f32 v18, -v84, v85, 1.0
	v_fmac_f32_e32 v85, v18, v85
	v_div_scale_f32 v18, vcc, 1.0, v60, 1.0
	v_mul_f32_e32 v19, v18, v85
	v_fma_f32 v86, -v84, v19, v18
	v_fmac_f32_e32 v19, v86, v85
	v_fma_f32 v18, -v84, v19, v18
	v_div_fmas_f32 v18, v18, v85, v19
	v_div_fixup_f32 v18, v18, v60, 1.0
	v_pk_mul_f32 v[32:33], v[32:33], v[18:19] op_sel_hi:[1,0]
	v_pk_mul_f32 v[28:29], v[28:29], v[18:19] op_sel_hi:[1,0]
	v_pk_mul_f32 v[32:33], v[16:17], v[32:33]
	v_pk_mul_f32 v[72:73], v[72:73], v[18:19] op_sel_hi:[1,0]
	v_pk_mul_f32 v[20:21], v[32:33], v[20:21]
	v_pk_mul_f32 v[32:33], v[74:75], v[18:19] op_sel_hi:[1,0]
	v_pk_mul_f32 v[74:75], v[78:79], v[18:19] op_sel_hi:[1,0]
	v_pk_mul_f32 v[70:71], v[70:71], v[18:19] op_sel_hi:[1,0]
	v_pk_mul_f32 v[74:75], v[12:13], v[74:75]
	v_pk_mul_f32 v[28:29], v[14:15], v[28:29]
	v_pk_mul_f32 v[22:23], v[74:75], v[22:23]
	v_pk_mul_f32 v[74:75], v[76:77], v[18:19] op_sel_hi:[1,0]
	v_pk_mul_f32 v[18:19], v[26:27], v[18:19] op_sel_hi:[1,0]
	v_pk_mul_f32 v[32:33], v[10:11], v[32:33]
	v_pk_mul_f32 v[74:75], v[6:7], v[74:75]
	v_pk_mul_f32 v[72:73], v[8:9], v[72:73]
	v_pk_mul_f32 v[70:71], v[2:3], v[70:71]
	v_pk_mul_f32 v[18:19], v[4:5], v[18:19]
	v_pk_mul_f32 v[28:29], v[28:29], v[82:83]
	v_pk_mul_f32 v[32:33], v[32:33], v[80:81]
	v_pk_mul_f32 v[68:69], v[74:75], v[68:69]
	v_pk_mul_f32 v[24:25], v[72:73], v[24:25]
	v_pk_mul_f32 v[66:67], v[70:71], v[66:67]
	v_pk_mul_f32 v[26:27], v[18:19], v[58:59]
	v_cvt_pk_bf16_f32 v18, v28, v29
	v_cvt_pk_bf16_f32 v19, v20, v21
	v_cvt_pk_bf16_f32 v20, v32, v33
	v_cvt_pk_bf16_f32 v21, v22, v23
	v_cvt_pk_bf16_f32 v22, v68, v69
	v_cvt_pk_bf16_f32 v23, v24, v25
	v_cvt_pk_bf16_f32 v24, v66, v67
	v_cvt_pk_bf16_f32 v25, v26, v27
	global_store_dwordx4 v[30:31], v[18:21], off
	global_store_dwordx4 v[30:31], v[22:25], off offset:16
	s_waitcnt vmcnt(4)
	v_mov_b64_e32 v[26:27], v[38:39]
	v_mov_b64_e32 v[30:31], v[34:35]
	s_waitcnt vmcnt(2)
	v_mov_b64_e32 v[18:19], v[46:47]
	v_mov_b64_e32 v[22:23], v[42:43]
	v_mov_b64_e32 v[28:29], v[40:41]
	v_mov_b64_e32 v[32:33], v[36:37]
	v_mov_b64_e32 v[20:21], v[48:49]
	v_mov_b64_e32 v[24:25], v[44:45]
	v_add_f32_e32 v120, v120, v121
	v_add_f32_e32 v122, v122, v123
	v_add_f32_e32 v124, v124, v125
	v_add_f32_e32 v126, v126, v127
	v_add_f32_e32 v120, v120, v122
	v_add_f32_e32 v124, v124, v126
	v_add_f32_e32 v120, v120, v124
	v_max_f32_e64 v120, |v120|, v128
	v_cndmask_b32_e64 v66, v51, v120, s[40:41]
	v_mov_b32_e32 v60, v65
	s_andn2_b64 exec, exec, s[44:45]
	s_cbranch_execz .LBB0_704
.LBB0_701:
	v_add_u32_e32 v65, s10, v60
	s_mov_b32 s0, 0x8000
	v_cmp_gt_i32_e32 vcc, s0, v65
	s_movk_i32 s0, 0x7fff
	v_cmp_lt_i32_e64 s[0:1], s0, v65
	s_or_b64 s[44:45], s[0:1], s[44:45]
	s_and_saveexec_b64 s[0:1], vcc
	s_cbranch_execz .LBB0_700
	v_ashrrev_i32_e32 v58, 1, v65
	v_mad_i64_i32 v[42:43], s[8:9], v58, s96, v[52:53]
	v_mov_b32_e32 v51, v1
	v_lshl_add_u64 v[38:39], v[42:43], 0, v[0:1]
	v_lshl_add_u64 v[46:47], v[42:43], 0, v[50:51]
	global_load_dwordx4 v[34:37], v[38:39], off offset:16
	s_nop 0
	global_load_dwordx4 v[38:41], v[38:39], off
	s_nop 0
	global_load_dwordx4 v[42:45], v[46:47], off offset:16
	s_nop 0
	global_load_dwordx4 v[46:49], v[46:47], off
	v_mov_b32_e32 v51, v66
	s_and_saveexec_b64 s[46:47], s[40:41]
	s_cbranch_execz .LBB0_699
	v_lshl_add_u32 v130, v58, 4, v131
	v_lshlrev_b32_e32 v129, 3, v130
	global_load_dwordx4 v[120:123], v129, s[98:99]
	global_load_dwordx4 v[124:127], v129, s[98:99] offset:16
	global_load_dword v128, v130, s[100:101]
	s_branch .LBB0_699

; #define LAS __attribute__((address_space(3)))
; __global__ void __launch_bounds__(NT, 2) fwd_megakernel(Params p) {
;     extern __shared__ __attribute__((aligned(16))) unsigned char lds_raw[];
;     LAS unsigned char* lds = (LAS unsigned char*)lds_raw;
;     cg::grid_group grid = cg::this_grid();
;     const int G = gridDim.x, bid = blockIdx.x;
	.amdhsa_kernel _Z14fwd_megakernel6Params
		.amdhsa_group_segment_fixed_size 0
		.amdhsa_private_segment_fixed_size 0
		.amdhsa_kernarg_size 400
		.amdhsa_user_sgpr_count 2
		.amdhsa_user_sgpr_dispatch_ptr 0
		.amdhsa_user_sgpr_queue_ptr 0
		.amdhsa_user_sgpr_kernarg_segment_ptr 1
		.amdhsa_user_sgpr_dispatch_id 0
		.amdhsa_user_sgpr_kernarg_preload_length 0
		.amdhsa_user_sgpr_kernarg_preload_offset 0
		.amdhsa_user_sgpr_private_segment_size 0
		.amdhsa_uses_dynamic_stack 0
		.amdhsa_enable_private_segment 0
		.amdhsa_system_sgpr_workgroup_id_x 1
		.amdhsa_system_sgpr_workgroup_id_y 0
		.amdhsa_system_sgpr_workgroup_id_z 0
		.amdhsa_system_sgpr_workgroup_info 0
		.amdhsa_system_vgpr_workitem_id 2
		.amdhsa_next_free_vgpr 253
		.amdhsa_next_free_sgpr 102
		.amdhsa_accum_offset 256
		.amdhsa_reserve_vcc 1
		.amdhsa_float_round_mode_32 0
		.amdhsa_float_round_mode_16_64 0
		.amdhsa_float_denorm_mode_32 3
		.amdhsa_float_denorm_mode_16_64 3
		.amdhsa_dx10_clamp 1
		.amdhsa_ieee_mode 1
		.amdhsa_fp16_overflow 0
		.amdhsa_tg_split 0
		.amdhsa_exception_fp_ieee_invalid_op 0
		.amdhsa_exception_fp_denorm_src 0
		.amdhsa_exception_fp_ieee_div_zero 0
		.amdhsa_exception_fp_ieee_overflow 0
		.amdhsa_exception_fp_ieee_underflow 0
		.amdhsa_exception_fp_ieee_inexact 0
		.amdhsa_exception_int_div_zero 0
	.end_amdhsa_kernel

; #define LAS __attribute__((address_space(3)))
; __global__ void __launch_bounds__(NT, 2) fwd_megakernel(Params p) {
;     extern __shared__ __attribute__((aligned(16))) unsigned char lds_raw[];
;     LAS unsigned char* lds = (LAS unsigned char*)lds_raw;
;     cg::grid_group grid = cg::this_grid();
;     const int G = gridDim.x, bid = blockIdx.x;
amdhsa.kernels:
  - .agpr_count:     0
    .args:
      - .offset:         0
        .size:           144
        .value_kind:     by_value
      - .offset:         144
        .size:           4
        .value_kind:     hidden_block_count_x
      - .offset:         148
        .size:           4
        .value_kind:     hidden_block_count_y
      - .offset:         152
        .size:           4
        .value_kind:     hidden_block_count_z
      - .offset:         156
        .size:           2
        .value_kind:     hidden_group_size_x
      - .offset:         158
        .size:           2
        .value_kind:     hidden_group_size_y
      - .offset:         160
        .size:           2
        .value_kind:     hidden_group_size_z
      - .offset:         162
        .size:           2
        .value_kind:     hidden_remainder_x
      - .offset:         164
        .size:           2
        .value_kind:     hidden_remainder_y
      - .offset:         166
        .size:           2
        .value_kind:     hidden_remainder_z
      - .offset:         184
        .size:           8
        .value_kind:     hidden_global_offset_x
      - .offset:         192
        .size:           8
        .value_kind:     hidden_global_offset_y
      - .offset:         200
        .size:           8
        .value_kind:     hidden_global_offset_z
      - .offset:         208
        .size:           2
        .value_kind:     hidden_grid_dims
      - .offset:         232
        .size:           8
        .value_kind:     hidden_multigrid_sync_arg
      - .offset:         264
        .size:           4
        .value_kind:     hidden_dynamic_lds_size
    .group_segment_fixed_size: 0
    .kernarg_segment_align: 8
    .kernarg_segment_size: 400
    .language:       OpenCL C
    .language_version:
      - 2
      - 0
    .max_flat_workgroup_size: 512
    .name:           _Z14fwd_megakernel6Params
    .private_segment_fixed_size: 0
    .sgpr_count:     108
    .sgpr_spill_count: 193
    .symbol:         _Z14fwd_megakernel6Params.kd
    .uniform_work_group_size: 1
    .uses_dynamic_stack: false
    .vgpr_count:     253
    .vgpr_spill_count: 0
    .wavefront_size: 64
